# experiment: O9S with the A-fragment registers of the P1 and P3 K-loops shifted by 2 (src1 bank phase 0 instead of 2)
# speedup vs baseline: 1.0017x; 1.0017x over previous
.LBB0_170:
	ds_read_b128 v[136:139], v191
	ds_read_b128 v[158:161], v191 offset:1024
	ds_read_b128 v[162:165], v191 offset:2048
	ds_read_b128 v[166:169], v191 offset:3072
	ds_read_b128 v[170:173], v192
	ds_read_b128 v[174:177], v192 offset:1024
	ds_read_b128 v[178:181], v192 offset:2048
	ds_read_b128 v[194:197], v192 offset:3072
	s_add_u32 s0, s42, 0xfff00080
	s_addc_u32 s50, s43, -1
	s_cmp_eq_u32 s70, 60
	s_cselect_b32 s53, s23, s50
	s_cselect_b32 s52, s41, s0
	s_cselect_b32 s51, s21, s68
	s_cselect_b32 s50, s66, s67
	s_add_i32 m0, s31, 0xc000
	ds_read_b128 v[200:203], v193
	ds_read_b128 v[204:207], v193 offset:1024
	ds_read_b128 v[208:211], v193 offset:2048
	ds_read_b128 v[212:215], v193 offset:3072
	ds_read_b128 v[216:219], v193 offset:4096
	ds_read_b128 v[220:223], v193 offset:5120
	ds_read_b128 v[224:227], v193 offset:6144
	ds_read_b128 v[228:231], v193 offset:7168
	global_load_lds_dwordx4 v152, s[42:43]
	s_add_i32 m0, s31, 0xe000
	s_nop 0
	global_load_lds_dwordx4 v154, s[42:43]
	s_waitcnt vmcnt(8)
	s_waitcnt lgkmcnt(0)
	s_setprio 1
	s_barrier
	v_mfma_f32_16x16x32_bf16 v[132:135], v[136:139], v[200:203], v[132:135]
	v_mfma_f32_16x16x32_bf16 v[132:135], v[158:161], v[204:207], v[132:135]
	v_mfma_f32_16x16x32_bf16 v[128:131], v[162:165], v[200:203], v[128:131]
	v_mfma_f32_16x16x32_bf16 v[128:131], v[166:169], v[204:207], v[128:131]
	v_mfma_f32_16x16x32_bf16 v[124:127], v[170:173], v[200:203], v[124:127]
	v_mfma_f32_16x16x32_bf16 v[124:127], v[174:177], v[204:207], v[124:127]
	v_mfma_f32_16x16x32_bf16 v[120:123], v[178:181], v[200:203], v[120:123]
	v_mfma_f32_16x16x32_bf16 v[120:123], v[194:197], v[204:207], v[120:123]
	v_mfma_f32_16x16x32_bf16 v[104:107], v[178:181], v[208:211], v[104:107]
	v_mfma_f32_16x16x32_bf16 v[104:107], v[194:197], v[212:215], v[104:107]
	v_mfma_f32_16x16x32_bf16 v[108:111], v[170:173], v[208:211], v[108:111]
	v_mfma_f32_16x16x32_bf16 v[108:111], v[174:177], v[212:215], v[108:111]
	v_mfma_f32_16x16x32_bf16 v[112:115], v[162:165], v[208:211], v[112:115]
	v_mfma_f32_16x16x32_bf16 v[112:115], v[166:169], v[212:215], v[112:115]
	v_mfma_f32_16x16x32_bf16 v[116:119], v[136:139], v[208:211], v[116:119]
	v_mfma_f32_16x16x32_bf16 v[116:119], v[158:161], v[212:215], v[116:119]
	v_mfma_f32_16x16x32_bf16 v[100:103], v[136:139], v[216:219], v[100:103]
	v_mfma_f32_16x16x32_bf16 v[100:103], v[158:161], v[220:223], v[100:103]
	v_mfma_f32_16x16x32_bf16 v[96:99], v[162:165], v[216:219], v[96:99]
	v_mfma_f32_16x16x32_bf16 v[96:99], v[166:169], v[220:223], v[96:99]
	v_mfma_f32_16x16x32_bf16 v[92:95], v[170:173], v[216:219], v[92:95]
	v_mfma_f32_16x16x32_bf16 v[92:95], v[174:177], v[220:223], v[92:95]
	v_mfma_f32_16x16x32_bf16 v[88:91], v[178:181], v[216:219], v[88:91]
	v_mfma_f32_16x16x32_bf16 v[88:91], v[194:197], v[220:223], v[88:91]
	v_mfma_f32_16x16x32_bf16 v[72:75], v[178:181], v[224:227], v[72:75]
	v_mfma_f32_16x16x32_bf16 v[72:75], v[194:197], v[228:231], v[72:75]
	v_mfma_f32_16x16x32_bf16 v[76:79], v[170:173], v[224:227], v[76:79]
	v_mfma_f32_16x16x32_bf16 v[76:79], v[174:177], v[228:231], v[76:79]
	v_mfma_f32_16x16x32_bf16 v[80:83], v[162:165], v[224:227], v[80:83]
	v_mfma_f32_16x16x32_bf16 v[80:83], v[166:169], v[228:231], v[80:83]
	v_mfma_f32_16x16x32_bf16 v[84:87], v[136:139], v[224:227], v[84:87]
	v_mfma_f32_16x16x32_bf16 v[84:87], v[158:161], v[228:231], v[84:87]
	s_setprio 0
	s_barrier
	s_add_i32 s0, s61, s19
	s_mov_b32 m0, s0
	ds_read_b128 v[200:203], v193 offset:16384
	ds_read_b128 v[204:207], v193 offset:17408
	ds_read_b128 v[208:211], v193 offset:18432
	ds_read_b128 v[212:215], v193 offset:19456
	ds_read_b128 v[216:219], v193 offset:20480
	ds_read_b128 v[220:223], v193 offset:21504
	ds_read_b128 v[224:227], v193 offset:22528
	ds_read_b128 v[228:231], v193 offset:23552
	global_load_lds_dwordx4 v142, s[50:51]
	s_add_i32 m0, s0, 0x2000
	s_add_u32 s72, s50, 0x100000
	s_addc_u32 s73, s51, 0
	s_add_i32 s0, s62, s19
	global_load_lds_dwordx4 v146, s[50:51]
	s_mov_b32 m0, s0
	s_nop 0
	global_load_lds_dwordx4 v142, s[72:73]
	s_add_i32 m0, s0, 0x2000
	s_nop 0
	global_load_lds_dwordx4 v146, s[72:73]
	s_mov_b32 m0, s31
	s_nop 0
	global_load_lds_dwordx4 v140, s[52:53]
	s_mov_b32 m0, s35
	s_nop 0
	global_load_lds_dwordx4 v144, s[52:53]
	s_waitcnt vmcnt(8)
	s_waitcnt lgkmcnt(0)
	s_setprio 1
	s_barrier
	v_mfma_f32_16x16x32_bf16 v[68:71], v[136:139], v[200:203], v[68:71]
	v_mfma_f32_16x16x32_bf16 v[68:71], v[158:161], v[204:207], v[68:71]
	v_mfma_f32_16x16x32_bf16 v[64:67], v[162:165], v[200:203], v[64:67]
	v_mfma_f32_16x16x32_bf16 v[64:67], v[166:169], v[204:207], v[64:67]
	v_mfma_f32_16x16x32_bf16 v[60:63], v[170:173], v[200:203], v[60:63]
	v_mfma_f32_16x16x32_bf16 v[60:63], v[174:177], v[204:207], v[60:63]
	v_mfma_f32_16x16x32_bf16 v[56:59], v[178:181], v[200:203], v[56:59]
	v_mfma_f32_16x16x32_bf16 v[56:59], v[194:197], v[204:207], v[56:59]
	v_mfma_f32_16x16x32_bf16 v[40:43], v[178:181], v[208:211], v[40:43]
	v_mfma_f32_16x16x32_bf16 v[40:43], v[194:197], v[212:215], v[40:43]
	v_mfma_f32_16x16x32_bf16 v[44:47], v[170:173], v[208:211], v[44:47]
	v_mfma_f32_16x16x32_bf16 v[44:47], v[174:177], v[212:215], v[44:47]
	v_mfma_f32_16x16x32_bf16 v[48:51], v[162:165], v[208:211], v[48:51]
	v_mfma_f32_16x16x32_bf16 v[48:51], v[166:169], v[212:215], v[48:51]
	v_mfma_f32_16x16x32_bf16 v[52:55], v[136:139], v[208:211], v[52:55]
	v_mfma_f32_16x16x32_bf16 v[52:55], v[158:161], v[212:215], v[52:55]
	v_mfma_f32_16x16x32_bf16 v[36:39], v[136:139], v[216:219], v[36:39]
	v_mfma_f32_16x16x32_bf16 v[36:39], v[158:161], v[220:223], v[36:39]
	v_mfma_f32_16x16x32_bf16 v[32:35], v[162:165], v[216:219], v[32:35]
	v_mfma_f32_16x16x32_bf16 v[32:35], v[166:169], v[220:223], v[32:35]
	v_mfma_f32_16x16x32_bf16 v[28:31], v[170:173], v[216:219], v[28:31]
	v_mfma_f32_16x16x32_bf16 v[28:31], v[174:177], v[220:223], v[28:31]
	v_mfma_f32_16x16x32_bf16 v[24:27], v[178:181], v[216:219], v[24:27]
	v_mfma_f32_16x16x32_bf16 v[24:27], v[194:197], v[220:223], v[24:27]
	v_mfma_f32_16x16x32_bf16 v[6:9], v[178:181], v[224:227], v[8:11]
	v_mfma_f32_16x16x32_bf16 v[6:9], v[194:197], v[228:231], v[6:9]
	v_mfma_f32_16x16x32_bf16 v[12:15], v[170:173], v[224:227], v[12:15]
	v_mfma_f32_16x16x32_bf16 v[12:15], v[174:177], v[228:231], v[12:15]
	v_mfma_f32_16x16x32_bf16 v[16:19], v[162:165], v[224:227], v[16:19]
	v_mfma_f32_16x16x32_bf16 v[16:19], v[166:169], v[228:231], v[16:19]
	v_mfma_f32_16x16x32_bf16 v[20:23], v[136:139], v[224:227], v[20:23]
	v_mfma_f32_16x16x32_bf16 v[20:23], v[158:161], v[228:231], v[20:23]
	s_setprio 0
	s_barrier
	s_add_i32 s0, 0, 0x18000
	v_add_u32_e32 v5, s0, v1
	s_add_i32 s71, 0, 0x1c000
	ds_read_b128 v[136:139], v5
	ds_read_b128 v[158:161], v5 offset:1024
	ds_read_b128 v[162:165], v5 offset:2048
	ds_read_b128 v[166:169], v5 offset:3072
	v_add_u32_e32 v5, s71, v1
	ds_read_b128 v[170:173], v5
	ds_read_b128 v[174:177], v5 offset:1024
	ds_read_b128 v[178:181], v5 offset:2048
	ds_read_b128 v[194:197], v5 offset:3072
	s_add_u32 s98, s52, 0x100000
	s_addc_u32 s99, s53, 0
	s_mov_b32 m0, s45
	ds_read_b128 v[200:203], v193 offset:32768
	ds_read_b128 v[204:207], v193 offset:33792
	ds_read_b128 v[208:211], v193 offset:34816
	ds_read_b128 v[212:215], v193 offset:35840
	ds_read_b128 v[216:219], v193 offset:36864
	ds_read_b128 v[220:223], v193 offset:37888
	ds_read_b128 v[224:227], v193 offset:38912
	ds_read_b128 v[228:231], v193 offset:39936
	global_load_lds_dwordx4 v140, s[98:99]
	s_mov_b32 m0, s46
	s_nop 0
	global_load_lds_dwordx4 v144, s[98:99]
	s_waitcnt vmcnt(8)
	s_waitcnt lgkmcnt(0)
	s_setprio 1
	s_barrier
	v_mfma_f32_16x16x32_bf16 v[132:135], v[136:139], v[200:203], v[132:135]
	v_mfma_f32_16x16x32_bf16 v[132:135], v[158:161], v[204:207], v[132:135]
	v_mfma_f32_16x16x32_bf16 v[128:131], v[162:165], v[200:203], v[128:131]
	v_mfma_f32_16x16x32_bf16 v[128:131], v[166:169], v[204:207], v[128:131]
	v_mfma_f32_16x16x32_bf16 v[124:127], v[170:173], v[200:203], v[124:127]
	v_mfma_f32_16x16x32_bf16 v[124:127], v[174:177], v[204:207], v[124:127]
	v_mfma_f32_16x16x32_bf16 v[120:123], v[178:181], v[200:203], v[120:123]
	v_mfma_f32_16x16x32_bf16 v[120:123], v[194:197], v[204:207], v[120:123]
	v_mfma_f32_16x16x32_bf16 v[104:107], v[178:181], v[208:211], v[104:107]
	v_mfma_f32_16x16x32_bf16 v[104:107], v[194:197], v[212:215], v[104:107]
	v_mfma_f32_16x16x32_bf16 v[108:111], v[170:173], v[208:211], v[108:111]
	v_mfma_f32_16x16x32_bf16 v[108:111], v[174:177], v[212:215], v[108:111]
	v_mfma_f32_16x16x32_bf16 v[112:115], v[162:165], v[208:211], v[112:115]
	v_mfma_f32_16x16x32_bf16 v[112:115], v[166:169], v[212:215], v[112:115]
	v_mfma_f32_16x16x32_bf16 v[116:119], v[136:139], v[208:211], v[116:119]
	v_mfma_f32_16x16x32_bf16 v[116:119], v[158:161], v[212:215], v[116:119]
	v_mfma_f32_16x16x32_bf16 v[100:103], v[136:139], v[216:219], v[100:103]
	v_mfma_f32_16x16x32_bf16 v[100:103], v[158:161], v[220:223], v[100:103]
	v_mfma_f32_16x16x32_bf16 v[96:99], v[162:165], v[216:219], v[96:99]
	v_mfma_f32_16x16x32_bf16 v[96:99], v[166:169], v[220:223], v[96:99]
	v_mfma_f32_16x16x32_bf16 v[92:95], v[170:173], v[216:219], v[92:95]
	v_mfma_f32_16x16x32_bf16 v[92:95], v[174:177], v[220:223], v[92:95]
	v_mfma_f32_16x16x32_bf16 v[88:91], v[178:181], v[216:219], v[88:91]
	v_mfma_f32_16x16x32_bf16 v[88:91], v[194:197], v[220:223], v[88:91]
	v_mfma_f32_16x16x32_bf16 v[72:75], v[178:181], v[224:227], v[72:75]
	v_mfma_f32_16x16x32_bf16 v[72:75], v[194:197], v[228:231], v[72:75]
	v_mfma_f32_16x16x32_bf16 v[76:79], v[170:173], v[224:227], v[76:79]
	v_mfma_f32_16x16x32_bf16 v[76:79], v[174:177], v[228:231], v[76:79]
	v_mfma_f32_16x16x32_bf16 v[80:83], v[162:165], v[224:227], v[80:83]
	v_mfma_f32_16x16x32_bf16 v[80:83], v[166:169], v[228:231], v[80:83]
	v_mfma_f32_16x16x32_bf16 v[84:87], v[136:139], v[224:227], v[84:87]
	v_mfma_f32_16x16x32_bf16 v[84:87], v[158:161], v[228:231], v[84:87]
	s_setprio 0
	s_barrier
	s_add_i32 s0, s0, s19
	s_add_i32 m0, s0, 0xffffff80
	ds_read_b128 v[200:203], v193 offset:49152
	ds_read_b128 v[204:207], v193 offset:50176
	ds_read_b128 v[208:211], v193 offset:51200
	ds_read_b128 v[212:215], v193 offset:52224
	ds_read_b128 v[216:219], v193 offset:53248
	ds_read_b128 v[220:223], v193 offset:54272
	ds_read_b128 v[224:227], v193 offset:55296
	ds_read_b128 v[228:231], v193 offset:56320
	global_load_lds_dwordx4 v142, s[50:51] offset:128
	s_add_i32 m0, s0, 0x1f80
	s_add_i32 s0, s71, s19
	global_load_lds_dwordx4 v146, s[50:51] offset:128
	s_add_u32 s50, s50, 0x100080
	s_addc_u32 s51, s51, 0
	s_mov_b32 m0, s0
	s_nop 0
	global_load_lds_dwordx4 v142, s[50:51]
	s_add_i32 m0, s0, 0x2000
	s_nop 0
	global_load_lds_dwordx4 v146, s[50:51]
	s_add_i32 m0, s56, 0xffffff80
	s_nop 0
	global_load_lds_dwordx4 v140, s[52:53] offset:128
	s_add_i32 m0, s57, 0xffffff80
	s_nop 0
	global_load_lds_dwordx4 v144, s[52:53] offset:128
	s_waitcnt vmcnt(8)
	s_waitcnt lgkmcnt(0)
	s_setprio 1
	s_barrier
	v_mfma_f32_16x16x32_bf16 v[68:71], v[136:139], v[200:203], v[68:71]
	v_mfma_f32_16x16x32_bf16 v[68:71], v[158:161], v[204:207], v[68:71]
	v_mfma_f32_16x16x32_bf16 v[64:67], v[162:165], v[200:203], v[64:67]
	v_mfma_f32_16x16x32_bf16 v[64:67], v[166:169], v[204:207], v[64:67]
	v_mfma_f32_16x16x32_bf16 v[60:63], v[170:173], v[200:203], v[60:63]
	v_mfma_f32_16x16x32_bf16 v[60:63], v[174:177], v[204:207], v[60:63]
	v_mfma_f32_16x16x32_bf16 v[56:59], v[178:181], v[200:203], v[56:59]
	v_mfma_f32_16x16x32_bf16 v[56:59], v[194:197], v[204:207], v[56:59]
	v_mfma_f32_16x16x32_bf16 v[52:55], v[136:139], v[208:211], v[52:55]
	v_mfma_f32_16x16x32_bf16 v[52:55], v[158:161], v[212:215], v[52:55]
	v_mfma_f32_16x16x32_bf16 v[48:51], v[162:165], v[208:211], v[48:51]
	v_mfma_f32_16x16x32_bf16 v[48:51], v[166:169], v[212:215], v[48:51]
	v_mfma_f32_16x16x32_bf16 v[44:47], v[170:173], v[208:211], v[44:47]
	v_mfma_f32_16x16x32_bf16 v[44:47], v[174:177], v[212:215], v[44:47]
	v_mfma_f32_16x16x32_bf16 v[40:43], v[178:181], v[208:211], v[40:43]
	v_mfma_f32_16x16x32_bf16 v[40:43], v[194:197], v[212:215], v[40:43]
	v_mfma_f32_16x16x32_bf16 v[36:39], v[136:139], v[216:219], v[36:39]
	v_mfma_f32_16x16x32_bf16 v[36:39], v[158:161], v[220:223], v[36:39]
	v_mfma_f32_16x16x32_bf16 v[32:35], v[162:165], v[216:219], v[32:35]
	v_mfma_f32_16x16x32_bf16 v[32:35], v[166:169], v[220:223], v[32:35]
	v_mfma_f32_16x16x32_bf16 v[28:31], v[170:173], v[216:219], v[28:31]
	v_mfma_f32_16x16x32_bf16 v[28:31], v[174:177], v[220:223], v[28:31]
	v_mfma_f32_16x16x32_bf16 v[24:27], v[178:181], v[216:219], v[24:27]
	v_mfma_f32_16x16x32_bf16 v[24:27], v[194:197], v[220:223], v[24:27]
	v_mfma_f32_16x16x32_bf16 v[20:23], v[136:139], v[224:227], v[20:23]
	v_mfma_f32_16x16x32_bf16 v[20:23], v[158:161], v[228:231], v[20:23]
	v_mfma_f32_16x16x32_bf16 v[16:19], v[162:165], v[224:227], v[16:19]
	v_mfma_f32_16x16x32_bf16 v[16:19], v[166:169], v[228:231], v[16:19]
	v_mfma_f32_16x16x32_bf16 v[10:13], v[170:173], v[224:227], v[12:15]
	v_mfma_f32_16x16x32_bf16 v[12:15], v[174:177], v[228:231], v[10:13]
	v_mfma_f32_16x16x32_bf16 v[6:9], v[178:181], v[224:227], v[6:9]
	v_mfma_f32_16x16x32_bf16 v[8:11], v[194:197], v[228:231], v[6:9]
	s_setprio 0
	s_barrier
	s_add_i32 s70, s70, 2
	s_add_u32 s42, s42, 0x100
	s_addc_u32 s43, s43, 0
	s_add_u32 s67, s67, 0x100
	s_addc_u32 s68, s68, 0
	s_cmp_gt_u32 s70, 61
	s_cbranch_scc0 .LBB0_170
	s_and_b64 vcc, exec, s[16:17]
	s_cbranch_vccz .LBB0_173
	s_barrier

.LBB0_429:
	ds_read_b128 v[150:153], v156
	ds_read_b128 v[162:165], v156 offset:1024
	ds_read_b128 v[166:169], v156 offset:2048
	ds_read_b128 v[170:173], v156 offset:3072
	ds_read_b128 v[174:177], v157
	ds_read_b128 v[178:181], v157 offset:1024
	ds_read_b128 v[182:185], v157 offset:2048
	ds_read_b128 v[186:189], v157 offset:3072
	s_add_u32 s0, s50, 0xfff00080
	s_addc_u32 s52, s51, -1
	s_cmp_eq_u32 s72, 60
	s_cselect_b32 s55, s27, s52
	s_cselect_b32 s54, s67, s0
	s_cselect_b32 s53, s25, s71
	s_cselect_b32 s52, s68, s70
	s_add_i32 m0, s43, 0xc000
	ds_read_b128 v[192:195], v158
	ds_read_b128 v[196:199], v158 offset:1024
	ds_read_b128 v[200:203], v158 offset:2048
	ds_read_b128 v[204:207], v158 offset:3072
	ds_read_b128 v[208:211], v158 offset:4096
	ds_read_b128 v[212:215], v158 offset:5120
	ds_read_b128 v[216:219], v158 offset:6144
	ds_read_b128 v[220:223], v158 offset:7168
	global_load_lds_dwordx4 v142, s[50:51]
	s_add_i32 m0, s43, 0xe000
	s_nop 0
	global_load_lds_dwordx4 v144, s[50:51]
	s_waitcnt vmcnt(8)
	s_waitcnt lgkmcnt(0)
	s_setprio 1
	s_barrier
	v_mfma_f32_16x16x32_bf16 v[128:131], v[150:153], v[192:195], v[128:131]
	v_mfma_f32_16x16x32_bf16 v[128:131], v[162:165], v[196:199], v[128:131]
	v_mfma_f32_16x16x32_bf16 v[124:127], v[166:169], v[192:195], v[124:127]
	v_mfma_f32_16x16x32_bf16 v[124:127], v[170:173], v[196:199], v[124:127]
	v_mfma_f32_16x16x32_bf16 v[120:123], v[174:177], v[192:195], v[120:123]
	v_mfma_f32_16x16x32_bf16 v[120:123], v[178:181], v[196:199], v[120:123]
	v_mfma_f32_16x16x32_bf16 v[116:119], v[182:185], v[192:195], v[116:119]
	v_mfma_f32_16x16x32_bf16 v[116:119], v[186:189], v[196:199], v[116:119]
	v_mfma_f32_16x16x32_bf16 v[100:103], v[182:185], v[200:203], v[100:103]
	v_mfma_f32_16x16x32_bf16 v[100:103], v[186:189], v[204:207], v[100:103]
	v_mfma_f32_16x16x32_bf16 v[104:107], v[174:177], v[200:203], v[104:107]
	v_mfma_f32_16x16x32_bf16 v[104:107], v[178:181], v[204:207], v[104:107]
	v_mfma_f32_16x16x32_bf16 v[108:111], v[166:169], v[200:203], v[108:111]
	v_mfma_f32_16x16x32_bf16 v[108:111], v[170:173], v[204:207], v[108:111]
	v_mfma_f32_16x16x32_bf16 v[112:115], v[150:153], v[200:203], v[112:115]
	v_mfma_f32_16x16x32_bf16 v[112:115], v[162:165], v[204:207], v[112:115]
	v_mfma_f32_16x16x32_bf16 v[96:99], v[150:153], v[208:211], v[96:99]
	v_mfma_f32_16x16x32_bf16 v[96:99], v[162:165], v[212:215], v[96:99]
	v_mfma_f32_16x16x32_bf16 v[92:95], v[166:169], v[208:211], v[92:95]
	v_mfma_f32_16x16x32_bf16 v[92:95], v[170:173], v[212:215], v[92:95]
	v_mfma_f32_16x16x32_bf16 v[88:91], v[174:177], v[208:211], v[88:91]
	v_mfma_f32_16x16x32_bf16 v[88:91], v[178:181], v[212:215], v[88:91]
	v_mfma_f32_16x16x32_bf16 v[84:87], v[182:185], v[208:211], v[84:87]
	v_mfma_f32_16x16x32_bf16 v[84:87], v[186:189], v[212:215], v[84:87]
	v_mfma_f32_16x16x32_bf16 v[68:71], v[182:185], v[216:219], v[68:71]
	v_mfma_f32_16x16x32_bf16 v[68:71], v[186:189], v[220:223], v[68:71]
	v_mfma_f32_16x16x32_bf16 v[72:75], v[174:177], v[216:219], v[72:75]
	v_mfma_f32_16x16x32_bf16 v[72:75], v[178:181], v[220:223], v[72:75]
	v_mfma_f32_16x16x32_bf16 v[76:79], v[166:169], v[216:219], v[76:79]
	v_mfma_f32_16x16x32_bf16 v[76:79], v[170:173], v[220:223], v[76:79]
	v_mfma_f32_16x16x32_bf16 v[80:83], v[150:153], v[216:219], v[80:83]
	v_mfma_f32_16x16x32_bf16 v[80:83], v[162:165], v[220:223], v[80:83]
	s_setprio 0
	s_barrier
	s_add_i32 s0, s62, s41
	s_mov_b32 m0, s0
	ds_read_b128 v[192:195], v158 offset:16384
	ds_read_b128 v[196:199], v158 offset:17408
	ds_read_b128 v[200:203], v158 offset:18432
	ds_read_b128 v[204:207], v158 offset:19456
	ds_read_b128 v[208:211], v158 offset:20480
	ds_read_b128 v[212:215], v158 offset:21504
	ds_read_b128 v[216:219], v158 offset:22528
	ds_read_b128 v[220:223], v158 offset:23552
	global_load_lds_dwordx4 v136, s[52:53]
	s_add_i32 m0, s0, 0x2000
	s_add_u32 s74, s52, 0x100000
	s_addc_u32 s75, s53, 0
	s_add_i32 s0, s63, s41
	global_load_lds_dwordx4 v140, s[52:53]
	s_mov_b32 m0, s0
	s_nop 0
	global_load_lds_dwordx4 v136, s[74:75]
	s_add_i32 m0, s0, 0x2000
	s_nop 0
	global_load_lds_dwordx4 v140, s[74:75]
	s_mov_b32 m0, s43
	s_nop 0
	global_load_lds_dwordx4 v134, s[54:55]
	s_mov_b32 m0, s48
	s_nop 0
	global_load_lds_dwordx4 v138, s[54:55]
	s_waitcnt vmcnt(8)
	s_waitcnt lgkmcnt(0)
	s_setprio 1
	s_barrier
	v_mfma_f32_16x16x32_bf16 v[64:67], v[150:153], v[192:195], v[64:67]
	v_mfma_f32_16x16x32_bf16 v[64:67], v[162:165], v[196:199], v[64:67]
	v_mfma_f32_16x16x32_bf16 v[60:63], v[166:169], v[192:195], v[60:63]
	v_mfma_f32_16x16x32_bf16 v[60:63], v[170:173], v[196:199], v[60:63]
	v_mfma_f32_16x16x32_bf16 v[56:59], v[174:177], v[192:195], v[56:59]
	v_mfma_f32_16x16x32_bf16 v[56:59], v[178:181], v[196:199], v[56:59]
	v_mfma_f32_16x16x32_bf16 v[52:55], v[182:185], v[192:195], v[52:55]
	v_mfma_f32_16x16x32_bf16 v[52:55], v[186:189], v[196:199], v[52:55]
	v_mfma_f32_16x16x32_bf16 v[36:39], v[182:185], v[200:203], v[36:39]
	v_mfma_f32_16x16x32_bf16 v[36:39], v[186:189], v[204:207], v[36:39]
	v_mfma_f32_16x16x32_bf16 v[40:43], v[174:177], v[200:203], v[40:43]
	v_mfma_f32_16x16x32_bf16 v[40:43], v[178:181], v[204:207], v[40:43]
	v_mfma_f32_16x16x32_bf16 v[44:47], v[166:169], v[200:203], v[44:47]
	v_mfma_f32_16x16x32_bf16 v[44:47], v[170:173], v[204:207], v[44:47]
	v_mfma_f32_16x16x32_bf16 v[48:51], v[150:153], v[200:203], v[48:51]
	v_mfma_f32_16x16x32_bf16 v[48:51], v[162:165], v[204:207], v[48:51]
	v_mfma_f32_16x16x32_bf16 v[32:35], v[150:153], v[208:211], v[32:35]
	v_mfma_f32_16x16x32_bf16 v[32:35], v[162:165], v[212:215], v[32:35]
	v_mfma_f32_16x16x32_bf16 v[28:31], v[166:169], v[208:211], v[28:31]
	v_mfma_f32_16x16x32_bf16 v[28:31], v[170:173], v[212:215], v[28:31]
	v_mfma_f32_16x16x32_bf16 v[24:27], v[174:177], v[208:211], v[24:27]
	v_mfma_f32_16x16x32_bf16 v[24:27], v[178:181], v[212:215], v[24:27]
	v_mfma_f32_16x16x32_bf16 v[20:23], v[182:185], v[208:211], v[20:23]
	v_mfma_f32_16x16x32_bf16 v[20:23], v[186:189], v[212:215], v[20:23]
	v_mfma_f32_16x16x32_bf16 v[4:7], v[182:185], v[216:219], v[4:7]
	v_mfma_f32_16x16x32_bf16 v[4:7], v[186:189], v[220:223], v[4:7]
	v_mfma_f32_16x16x32_bf16 v[8:11], v[174:177], v[216:219], v[8:11]
	v_mfma_f32_16x16x32_bf16 v[8:11], v[178:181], v[220:223], v[8:11]
	v_mfma_f32_16x16x32_bf16 v[12:15], v[166:169], v[216:219], v[12:15]
	v_mfma_f32_16x16x32_bf16 v[12:15], v[170:173], v[220:223], v[12:15]
	v_mfma_f32_16x16x32_bf16 v[16:19], v[150:153], v[216:219], v[16:19]
	v_mfma_f32_16x16x32_bf16 v[16:19], v[162:165], v[220:223], v[16:19]
	s_setprio 0
	s_barrier
	s_add_i32 s0, 0, 0x18000
	v_add_u32_e32 v161, s0, v133
	s_add_i32 s73, 0, 0x1c000
	ds_read_b128 v[150:153], v161
	ds_read_b128 v[162:165], v161 offset:1024
	ds_read_b128 v[166:169], v161 offset:2048
	ds_read_b128 v[170:173], v161 offset:3072
	v_add_u32_e32 v161, s73, v133
	ds_read_b128 v[174:177], v161
	ds_read_b128 v[178:181], v161 offset:1024
	ds_read_b128 v[182:185], v161 offset:2048
	ds_read_b128 v[186:189], v161 offset:3072
	s_add_u32 s98, s54, 0x100000
	s_addc_u32 s99, s55, 0
	s_mov_b32 m0, s49
	ds_read_b128 v[192:195], v158 offset:32768
	ds_read_b128 v[196:199], v158 offset:33792
	ds_read_b128 v[200:203], v158 offset:34816
	ds_read_b128 v[204:207], v158 offset:35840
	ds_read_b128 v[208:211], v158 offset:36864
	ds_read_b128 v[212:215], v158 offset:37888
	ds_read_b128 v[216:219], v158 offset:38912
	ds_read_b128 v[220:223], v158 offset:39936
	global_load_lds_dwordx4 v134, s[98:99]
	s_mov_b32 m0, s56
	s_nop 0
	global_load_lds_dwordx4 v138, s[98:99]
	s_waitcnt vmcnt(8)
	s_waitcnt lgkmcnt(0)
	s_setprio 1
	s_barrier
	v_mfma_f32_16x16x32_bf16 v[128:131], v[150:153], v[192:195], v[128:131]
	v_mfma_f32_16x16x32_bf16 v[128:131], v[162:165], v[196:199], v[128:131]
	v_mfma_f32_16x16x32_bf16 v[124:127], v[166:169], v[192:195], v[124:127]
	v_mfma_f32_16x16x32_bf16 v[124:127], v[170:173], v[196:199], v[124:127]
	v_mfma_f32_16x16x32_bf16 v[120:123], v[174:177], v[192:195], v[120:123]
	v_mfma_f32_16x16x32_bf16 v[120:123], v[178:181], v[196:199], v[120:123]
	v_mfma_f32_16x16x32_bf16 v[116:119], v[182:185], v[192:195], v[116:119]
	v_mfma_f32_16x16x32_bf16 v[116:119], v[186:189], v[196:199], v[116:119]
	v_mfma_f32_16x16x32_bf16 v[100:103], v[182:185], v[200:203], v[100:103]
	v_mfma_f32_16x16x32_bf16 v[100:103], v[186:189], v[204:207], v[100:103]
	v_mfma_f32_16x16x32_bf16 v[104:107], v[174:177], v[200:203], v[104:107]
	v_mfma_f32_16x16x32_bf16 v[104:107], v[178:181], v[204:207], v[104:107]
	v_mfma_f32_16x16x32_bf16 v[108:111], v[166:169], v[200:203], v[108:111]
	v_mfma_f32_16x16x32_bf16 v[108:111], v[170:173], v[204:207], v[108:111]
	v_mfma_f32_16x16x32_bf16 v[112:115], v[150:153], v[200:203], v[112:115]
	v_mfma_f32_16x16x32_bf16 v[112:115], v[162:165], v[204:207], v[112:115]
	v_mfma_f32_16x16x32_bf16 v[96:99], v[150:153], v[208:211], v[96:99]
	v_mfma_f32_16x16x32_bf16 v[96:99], v[162:165], v[212:215], v[96:99]
	v_mfma_f32_16x16x32_bf16 v[92:95], v[166:169], v[208:211], v[92:95]
	v_mfma_f32_16x16x32_bf16 v[92:95], v[170:173], v[212:215], v[92:95]
	v_mfma_f32_16x16x32_bf16 v[88:91], v[174:177], v[208:211], v[88:91]
	v_mfma_f32_16x16x32_bf16 v[88:91], v[178:181], v[212:215], v[88:91]
	v_mfma_f32_16x16x32_bf16 v[84:87], v[182:185], v[208:211], v[84:87]
	v_mfma_f32_16x16x32_bf16 v[84:87], v[186:189], v[212:215], v[84:87]
	v_mfma_f32_16x16x32_bf16 v[68:71], v[182:185], v[216:219], v[68:71]
	v_mfma_f32_16x16x32_bf16 v[68:71], v[186:189], v[220:223], v[68:71]
	v_mfma_f32_16x16x32_bf16 v[72:75], v[174:177], v[216:219], v[72:75]
	v_mfma_f32_16x16x32_bf16 v[72:75], v[178:181], v[220:223], v[72:75]
	v_mfma_f32_16x16x32_bf16 v[76:79], v[166:169], v[216:219], v[76:79]
	v_mfma_f32_16x16x32_bf16 v[76:79], v[170:173], v[220:223], v[76:79]
	v_mfma_f32_16x16x32_bf16 v[80:83], v[150:153], v[216:219], v[80:83]
	v_mfma_f32_16x16x32_bf16 v[80:83], v[162:165], v[220:223], v[80:83]
	s_setprio 0
	s_barrier
	s_add_i32 s0, s0, s41
	s_add_i32 m0, s0, 0xffffff80
	ds_read_b128 v[192:195], v158 offset:49152
	ds_read_b128 v[196:199], v158 offset:50176
	ds_read_b128 v[200:203], v158 offset:51200
	ds_read_b128 v[204:207], v158 offset:52224
	ds_read_b128 v[208:211], v158 offset:53248
	ds_read_b128 v[212:215], v158 offset:54272
	ds_read_b128 v[216:219], v158 offset:55296
	ds_read_b128 v[220:223], v158 offset:56320
	global_load_lds_dwordx4 v136, s[52:53] offset:128
	s_add_i32 m0, s0, 0x1f80
	s_add_i32 s0, s73, s41
	global_load_lds_dwordx4 v140, s[52:53] offset:128
	s_add_u32 s52, s52, 0x100080
	s_addc_u32 s53, s53, 0
	s_mov_b32 m0, s0
	s_nop 0
	global_load_lds_dwordx4 v136, s[52:53]
	s_add_i32 m0, s0, 0x2000
	s_nop 0
	global_load_lds_dwordx4 v140, s[52:53]
	s_add_i32 m0, s59, 0xffffff80
	s_nop 0
	global_load_lds_dwordx4 v134, s[54:55] offset:128
	s_add_i32 m0, s60, 0xffffff80
	s_nop 0
	global_load_lds_dwordx4 v138, s[54:55] offset:128
	s_waitcnt vmcnt(8)
	s_waitcnt lgkmcnt(0)
	s_setprio 1
	s_barrier
	v_mfma_f32_16x16x32_bf16 v[64:67], v[150:153], v[192:195], v[64:67]
	v_mfma_f32_16x16x32_bf16 v[64:67], v[162:165], v[196:199], v[64:67]
	v_mfma_f32_16x16x32_bf16 v[60:63], v[166:169], v[192:195], v[60:63]
	v_mfma_f32_16x16x32_bf16 v[60:63], v[170:173], v[196:199], v[60:63]
	v_mfma_f32_16x16x32_bf16 v[56:59], v[174:177], v[192:195], v[56:59]
	v_mfma_f32_16x16x32_bf16 v[56:59], v[178:181], v[196:199], v[56:59]
	v_mfma_f32_16x16x32_bf16 v[52:55], v[182:185], v[192:195], v[52:55]
	v_mfma_f32_16x16x32_bf16 v[52:55], v[186:189], v[196:199], v[52:55]
	v_mfma_f32_16x16x32_bf16 v[36:39], v[182:185], v[200:203], v[36:39]
	v_mfma_f32_16x16x32_bf16 v[36:39], v[186:189], v[204:207], v[36:39]
	v_mfma_f32_16x16x32_bf16 v[40:43], v[174:177], v[200:203], v[40:43]
	v_mfma_f32_16x16x32_bf16 v[40:43], v[178:181], v[204:207], v[40:43]
	v_mfma_f32_16x16x32_bf16 v[44:47], v[166:169], v[200:203], v[44:47]
	v_mfma_f32_16x16x32_bf16 v[44:47], v[170:173], v[204:207], v[44:47]
	v_mfma_f32_16x16x32_bf16 v[48:51], v[150:153], v[200:203], v[48:51]
	v_mfma_f32_16x16x32_bf16 v[48:51], v[162:165], v[204:207], v[48:51]
	v_mfma_f32_16x16x32_bf16 v[32:35], v[150:153], v[208:211], v[32:35]
	v_mfma_f32_16x16x32_bf16 v[32:35], v[162:165], v[212:215], v[32:35]
	v_mfma_f32_16x16x32_bf16 v[28:31], v[166:169], v[208:211], v[28:31]
	v_mfma_f32_16x16x32_bf16 v[28:31], v[170:173], v[212:215], v[28:31]
	v_mfma_f32_16x16x32_bf16 v[24:27], v[174:177], v[208:211], v[24:27]
	v_mfma_f32_16x16x32_bf16 v[24:27], v[178:181], v[212:215], v[24:27]
	v_mfma_f32_16x16x32_bf16 v[20:23], v[182:185], v[208:211], v[20:23]
	v_mfma_f32_16x16x32_bf16 v[20:23], v[186:189], v[212:215], v[20:23]
	v_mfma_f32_16x16x32_bf16 v[4:7], v[182:185], v[216:219], v[4:7]
	v_mfma_f32_16x16x32_bf16 v[4:7], v[186:189], v[220:223], v[4:7]
	v_mfma_f32_16x16x32_bf16 v[8:11], v[174:177], v[216:219], v[8:11]
	v_mfma_f32_16x16x32_bf16 v[8:11], v[178:181], v[220:223], v[8:11]
	v_mfma_f32_16x16x32_bf16 v[12:15], v[166:169], v[216:219], v[12:15]
	v_mfma_f32_16x16x32_bf16 v[12:15], v[170:173], v[220:223], v[12:15]
	v_mfma_f32_16x16x32_bf16 v[16:19], v[150:153], v[216:219], v[16:19]
	v_mfma_f32_16x16x32_bf16 v[16:19], v[162:165], v[220:223], v[16:19]
	s_setprio 0
	s_barrier
	s_add_i32 s72, s72, 2
	s_add_u32 s50, s50, 0x100
	s_addc_u32 s51, s51, 0
	s_add_u32 s70, s70, 0x100
	s_addc_u32 s71, s71, 0
	s_cmp_gt_u32 s72, 61
	s_cbranch_scc0 .LBB0_429
	s_and_b64 vcc, exec, s[22:23]
	s_cbranch_vccz .LBB0_432
	s_barrier
